# k48: k46 + P1s token-shift loop processes four rows per trip (all loads issued first), divisions as rcp+mul
# speedup vs baseline: 1.0048x; 1.0048x over previous
.Lp1s_quad:
	s_mul_i32 s36, s90, 3
	s_add_i32 s36, s36, s18
	s_cmp_gt_i32 s36, 0xffff
	s_cbranch_scc1 .LBB0_258
	s_add_u32 s38, s8, s10
	s_addc_u32 s39, s9, s11
	s_add_u32 s40, s38, s10
	s_addc_u32 s41, s39, s11
	s_add_u32 s42, s40, s10
	s_addc_u32 s43, s41, s11
	s_mov_b32 s37, s18
	s_and_b32 s0, s37, 0x1fff
	s_cmp_eq_u32 s0, 0
	s_cselect_b64 s[52:53], -1, 0
	s_cselect_b32 s0, 0, 0xfffffe00
	s_cselect_b32 s1, 0, -1
	s_add_u32 s44, s8, s0
	s_addc_u32 s45, s9, s1
	s_add_i32 s37, s37, s90
	s_and_b32 s0, s37, 0x1fff
	s_cmp_eq_u32 s0, 0
	s_cselect_b64 s[58:59], -1, 0
	s_cselect_b32 s0, 0, 0xfffffe00
	s_cselect_b32 s1, 0, -1
	s_add_u32 s46, s38, s0
	s_addc_u32 s47, s39, s1
	s_add_i32 s37, s37, s90
	s_and_b32 s0, s37, 0x1fff
	s_cmp_eq_u32 s0, 0
	s_cselect_b64 s[64:65], -1, 0
	s_cselect_b32 s0, 0, 0xfffffe00
	s_cselect_b32 s1, 0, -1
	s_add_u32 s48, s40, s0
	s_addc_u32 s49, s41, s1
	s_add_i32 s37, s37, s90
	s_and_b32 s0, s37, 0x1fff
	s_cmp_eq_u32 s0, 0
	s_cselect_b64 s[66:67], -1, 0
	s_cselect_b32 s0, 0, 0xfffffe00
	s_cselect_b32 s1, 0, -1
	s_add_u32 s50, s42, s0
	s_addc_u32 s51, s43, s1
	s_add_i32 s37, s37, s90
	global_load_dword v28, v0, s[8:9]
	global_load_dword v32, v4, s[44:45]
	global_load_dword v29, v0, s[38:39]
	global_load_dword v33, v4, s[46:47]
	global_load_dword v30, v0, s[40:41]
	global_load_dword v34, v4, s[48:49]
	global_load_dword v31, v0, s[42:43]
	global_load_dword v35, v4, s[50:51]
	s_waitcnt vmcnt(6)
	v_lshlrev_b32_e32 v7, 16, v28
	v_and_b32_e32 v6, 0xffff0000, v28
	v_lshlrev_b32_e32 v9, 16, v32
	v_and_b32_e32 v8, 0xffff0000, v32
	v_pk_add_f32 v[8:9], v[6:7], v[8:9]
	s_nop 0
	v_cndmask_b32_e64 v7, v9, v7, s[52:53]
	v_cndmask_b32_e64 v6, v8, v6, s[52:53]
	s_and_saveexec_b64 s[0:1], s[6:7]
	v_add_f32_e32 v7, v7, v7
	v_add_f32_e32 v6, v6, v6
	v_mul_f32_e32 v7, 0x3fb8aa3b, v7
	v_mul_f32_e32 v6, 0x3fb8aa3b, v6
	v_exp_f32_e32 v7, v7
	v_exp_f32_e32 v6, v6
	s_nop 0
	v_pk_add_f32 v[6:7], v[6:7], 1.0 op_sel_hi:[1,0]
	s_nop 0
	v_rcp_f32_e32 v8, v7
	s_nop 0
	v_mul_f32_e32 v7, -2.0, v8
	v_rcp_f32_e32 v8, v6
	s_nop 0
	v_mul_f32_e32 v6, -2.0, v8
	v_pk_add_f32 v[6:7], v[6:7], 1.0 op_sel_hi:[1,0]
	s_or_b64 exec, exec, s[0:1]
	s_nop 0
	v_cvt_pk_bf16_f32 v6, v7, v6
	global_store_dword v[2:3], v6, off
	v_lshl_add_u64 v[2:3], v[2:3], 0, s[4:5]
	s_waitcnt vmcnt(5)
	v_lshlrev_b32_e32 v7, 16, v29
	v_and_b32_e32 v6, 0xffff0000, v29
	v_lshlrev_b32_e32 v9, 16, v33
	v_and_b32_e32 v8, 0xffff0000, v33
	v_pk_add_f32 v[8:9], v[6:7], v[8:9]
	s_nop 0
	v_cndmask_b32_e64 v7, v9, v7, s[58:59]
	v_cndmask_b32_e64 v6, v8, v6, s[58:59]
	s_and_saveexec_b64 s[0:1], s[6:7]
	v_add_f32_e32 v7, v7, v7
	v_add_f32_e32 v6, v6, v6
	v_mul_f32_e32 v7, 0x3fb8aa3b, v7
	v_mul_f32_e32 v6, 0x3fb8aa3b, v6
	v_exp_f32_e32 v7, v7
	v_exp_f32_e32 v6, v6
	s_nop 0
	v_pk_add_f32 v[6:7], v[6:7], 1.0 op_sel_hi:[1,0]
	s_nop 0
	v_rcp_f32_e32 v8, v7
	s_nop 0
	v_mul_f32_e32 v7, -2.0, v8
	v_rcp_f32_e32 v8, v6
	s_nop 0
	v_mul_f32_e32 v6, -2.0, v8
	v_pk_add_f32 v[6:7], v[6:7], 1.0 op_sel_hi:[1,0]
	s_or_b64 exec, exec, s[0:1]
	s_nop 0
	v_cvt_pk_bf16_f32 v6, v7, v6
	global_store_dword v[2:3], v6, off
	v_lshl_add_u64 v[2:3], v[2:3], 0, s[4:5]
	s_waitcnt vmcnt(4)
	v_lshlrev_b32_e32 v7, 16, v30
	v_and_b32_e32 v6, 0xffff0000, v30
	v_lshlrev_b32_e32 v9, 16, v34
	v_and_b32_e32 v8, 0xffff0000, v34
	v_pk_add_f32 v[8:9], v[6:7], v[8:9]
	s_nop 0
	v_cndmask_b32_e64 v7, v9, v7, s[64:65]
	v_cndmask_b32_e64 v6, v8, v6, s[64:65]
	s_and_saveexec_b64 s[0:1], s[6:7]
	v_add_f32_e32 v7, v7, v7
	v_add_f32_e32 v6, v6, v6
	v_mul_f32_e32 v7, 0x3fb8aa3b, v7
	v_mul_f32_e32 v6, 0x3fb8aa3b, v6
	v_exp_f32_e32 v7, v7
	v_exp_f32_e32 v6, v6
	s_nop 0
	v_pk_add_f32 v[6:7], v[6:7], 1.0 op_sel_hi:[1,0]
	s_nop 0
	v_rcp_f32_e32 v8, v7
	s_nop 0
	v_mul_f32_e32 v7, -2.0, v8
	v_rcp_f32_e32 v8, v6
	s_nop 0
	v_mul_f32_e32 v6, -2.0, v8
	v_pk_add_f32 v[6:7], v[6:7], 1.0 op_sel_hi:[1,0]
	s_or_b64 exec, exec, s[0:1]
	s_nop 0
	v_cvt_pk_bf16_f32 v6, v7, v6
	global_store_dword v[2:3], v6, off
	v_lshl_add_u64 v[2:3], v[2:3], 0, s[4:5]
	s_waitcnt vmcnt(3)
	v_lshlrev_b32_e32 v7, 16, v31
	v_and_b32_e32 v6, 0xffff0000, v31
	v_lshlrev_b32_e32 v9, 16, v35
	v_and_b32_e32 v8, 0xffff0000, v35
	v_pk_add_f32 v[8:9], v[6:7], v[8:9]
	s_nop 0
	v_cndmask_b32_e64 v7, v9, v7, s[66:67]
	v_cndmask_b32_e64 v6, v8, v6, s[66:67]
	s_and_saveexec_b64 s[0:1], s[6:7]
	v_add_f32_e32 v7, v7, v7
	v_add_f32_e32 v6, v6, v6
	v_mul_f32_e32 v7, 0x3fb8aa3b, v7
	v_mul_f32_e32 v6, 0x3fb8aa3b, v6
	v_exp_f32_e32 v7, v7
	v_exp_f32_e32 v6, v6
	s_nop 0
	v_pk_add_f32 v[6:7], v[6:7], 1.0 op_sel_hi:[1,0]
	s_nop 0
	v_rcp_f32_e32 v8, v7
	s_nop 0
	v_mul_f32_e32 v7, -2.0, v8
	v_rcp_f32_e32 v8, v6
	s_nop 0
	v_mul_f32_e32 v6, -2.0, v8
	v_pk_add_f32 v[6:7], v[6:7], 1.0 op_sel_hi:[1,0]
	s_or_b64 exec, exec, s[0:1]
	s_nop 0
	v_cvt_pk_bf16_f32 v6, v7, v6
	global_store_dword v[2:3], v6, off
	v_lshl_add_u64 v[2:3], v[2:3], 0, s[4:5]
	s_mov_b32 s18, s37
	s_add_u32 s8, s42, s10
	s_addc_u32 s9, s43, s11
	s_cmp_gt_i32 s18, 0xffff
	s_cbranch_scc0 .Lp1s_quad
	s_branch .LBB0_260
